# as the helper-priority version but with exact per-use LDS waits (no coalescing)
# speedup vs baseline: 1.0025x; 1.0025x over previous
.Lmy_ck_nz:
	s_mov_b32 s100, 0xe000
	s_cmp_eq_u32 s23, 0
	s_cselect_b32 s100, 0x1c000, s100
	s_mov_b32 s101, 0x12e00
	s_cselect_b32 s101, 0x22100, s101
	s_lshl_b32 s96, s23, 13
	s_add_i32 s97, s96, 0x18000
	s_add_i32 s96, s96, 0xa000
	v_add_u32_e32 v225, s100, v1
	v_add_u32_e32 v236, s100, v0
	v_add_u32_e32 v226, s100, v2
	v_add_u32_e32 v227, s100, v3
	v_add_u32_e32 v228, s100, v4
	v_add_u32_e32 v229, s100, v5
	v_add_u32_e32 v237, s100, v6
	v_add_u32_e32 v238, s100, v7
	v_add_u32_e32 v230, s96, v8
	v_add_u32_e32 v239, s96, v9
	v_add_u32_e32 v231, s97, v8
	v_add_u32_e32 v26, s101, v1
	v_add_u32_e32 v27, s101, v0
	v_add_u32_e32 v28, s101, v2
	v_add_u32_e32 v29, s101, v3
	v_add_u32_e32 v30, s101, v4
	v_add_u32_e32 v31, s101, v5
	v_add_u32_e32 v32, s101, v6
	v_add_u32_e32 v33, s101, v7
	ds_read_b64 v[80:81], v237
	ds_read_b64 v[82:83], v238
	ds_read_b32 v84, v230
	ds_read_b32 v85, v230 offset:256
	ds_read_b32 v86, v230 offset:512
	ds_read_b32 v87, v230 offset:768
	ds_read_b32 v36, v239
	ds_read_b32 v37, v239 offset:256
	ds_read_b128 v[88:91], v225
	ds_read_b128 v[92:95], v225 offset:1024
	ds_read_b128 v[96:99], v225 offset:2048
	ds_read_b128 v[100:103], v225 offset:3072
	ds_read_b32 v104, v227 offset:4
	ds_read_b32 v105, v227 offset:76
	ds_read_b64 v[106:107], v227 offset:8
	ds_read_b64 v[108:109], v227 offset:40
	ds_read_b32 v126, v229 offset:4
	ds_read_b32 v127, v229 offset:76
	ds_read_b64 v[128:129], v229 offset:8
	ds_read_b64 v[130:131], v229 offset:40
	ds_read_b64 v[110:111], v228
	ds_read_b64 v[112:113], v228 offset:32
	ds_read_b64 v[114:115], v228 offset:64
	ds_read_b64 v[116:117], v228 offset:96
	ds_read_b64 v[118:119], v228 offset:8
	ds_read_b64 v[120:121], v228 offset:40
	ds_read_b64 v[122:123], v228 offset:72
	ds_read_b64 v[124:125], v228 offset:104
	s_waitcnt lgkmcnt(15)
	v_mfma_f32_16x16x4_f32 v[240:243], v80, v36, 0
	v_mfma_f32_16x16x4_f32 v[240:243], v81, v37, v[240:243]
	v_mfma_f32_16x16x4_f32 v[240:243], v88, v208, v[240:243]
	ds_read_b128 v[184:187], v236 offset:4096
	ds_read_b128 v[188:191], v236 offset:5120
	v_mfma_f32_16x16x4_f32 v[244:247], v89, v209, 0
	ds_read_b128 v[192:195], v236 offset:6144
	ds_read_b128 v[196:199], v236 offset:7168
	v_mfma_f32_16x16x4_f32 v[240:243], v90, v210, v[240:243]
	ds_read_b64 v[132:133], v237 offset:9984
	ds_read_b64 v[134:135], v238 offset:9984
	v_mfma_f32_16x16x4_f32 v[244:247], v91, v211, v[244:247]
	ds_read_b32 v136, v230 offset:2048
	ds_read_b32 v137, v230 offset:2304
	v_mfma_f32_16x16x4_f32 v[240:243], v92, v212, v[240:243]
	ds_read_b32 v138, v230 offset:2560
	ds_read_b32 v139, v230 offset:2816
	v_mfma_f32_16x16x4_f32 v[244:247], v93, v213, v[244:247]
	ds_read_b32 v38, v239 offset:2048
	ds_read_b32 v39, v239 offset:2304
	v_mfma_f32_16x16x4_f32 v[240:243], v94, v214, v[240:243]
	ds_read_b128 v[140:143], v225 offset:9984
	ds_read_b128 v[144:147], v225 offset:11008
	v_mfma_f32_16x16x4_f32 v[244:247], v95, v215, v[244:247]
	ds_read_b128 v[148:151], v225 offset:12032
	ds_read_b128 v[152:155], v225 offset:13056
	v_mfma_f32_16x16x4_f32 v[240:243], v96, v216, v[240:243]
	ds_read_b32 v156, v227 offset:9988
	ds_read_b32 v157, v227 offset:10060
	v_mfma_f32_16x16x4_f32 v[244:247], v97, v217, v[244:247]
	ds_read_b64 v[158:159], v227 offset:9992
	ds_read_b64 v[160:161], v227 offset:10024
	v_mfma_f32_16x16x4_f32 v[240:243], v98, v218, v[240:243]
	ds_read_b32 v178, v229 offset:9988
	ds_read_b32 v179, v229 offset:10060
	v_mfma_f32_16x16x4_f32 v[244:247], v99, v219, v[244:247]
	ds_read_b64 v[180:181], v229 offset:9992
	ds_read_b64 v[182:183], v229 offset:10024
	v_mfma_f32_16x16x4_f32 v[240:243], v100, v220, v[240:243]
	ds_read_b64 v[162:163], v228 offset:9984
	ds_read_b64 v[164:165], v228 offset:10016
	v_mfma_f32_16x16x4_f32 v[244:247], v101, v221, v[244:247]
	ds_read_b64 v[166:167], v228 offset:10048
	ds_read_b64 v[168:169], v228 offset:10080
	v_mfma_f32_16x16x4_f32 v[240:243], v102, v222, v[240:243]
	ds_read_b64 v[170:171], v228 offset:9992
	ds_read_b64 v[172:173], v228 offset:10024
	v_mfma_f32_16x16x4_f32 v[244:247], v103, v223, v[244:247]
	ds_read_b64 v[174:175], v228 offset:10056
	ds_read_b64 v[176:177], v228 offset:10088
	s_nop 7
	v_pk_add_f32 v[240:241], v[240:241], v[244:245]
	v_pk_add_f32 v[242:243], v[242:243], v[246:247]
	v_fmac_f32_e32 v241, v104, v240
	s_waitcnt lgkmcnt(15)
	v_pk_fma_f32 v[242:243], v[106:107], v[240:241], v[242:243] op_sel:[0,0,0] op_sel_hi:[1,0,1]
	v_pk_fma_f32 v[242:243], v[108:109], v[240:241], v[242:243] op_sel:[0,1,0] op_sel_hi:[1,1,1]
	v_fmac_f32_e32 v243, v105, v242
	ds_bpermute_b32 v204, v232, v240
	ds_bpermute_b32 v205, v232, v241
	ds_bpermute_b32 v206, v232, v242
	ds_bpermute_b32 v207, v232, v243
	ds_read_b128 v[88:91], v226
	ds_read_b128 v[92:95], v226 offset:64
	ds_read_b128 v[96:99], v226 offset:128
	ds_read_b128 v[100:103], v226 offset:192
	v_mfma_f32_16x16x4_f32 v[72:75], v132, v38, 0
	v_mfma_f32_16x16x4_f32 v[72:75], v133, v39, v[72:75]
	s_waitcnt lgkmcnt(6)
	v_pk_fma_f32 v[240:241], v[110:111], v[204:205], v[240:241] op_sel:[0,0,0] op_sel_hi:[1,0,1]
	v_pk_fma_f32 v[240:241], v[112:113], v[204:205], v[240:241] op_sel:[0,1,0] op_sel_hi:[1,1,1]
	s_waitcnt lgkmcnt(4)
	v_pk_fma_f32 v[240:241], v[114:115], v[206:207], v[240:241] op_sel:[0,0,0] op_sel_hi:[1,0,1]
	v_pk_fma_f32 v[240:241], v[116:117], v[206:207], v[240:241] op_sel:[0,1,0] op_sel_hi:[1,1,1]
	v_pk_fma_f32 v[242:243], v[118:119], v[204:205], v[242:243] op_sel:[0,0,0] op_sel_hi:[1,0,1]
	v_pk_fma_f32 v[242:243], v[120:121], v[204:205], v[242:243] op_sel:[0,1,0] op_sel_hi:[1,1,1]
	v_pk_fma_f32 v[242:243], v[122:123], v[206:207], v[242:243] op_sel:[0,0,0] op_sel_hi:[1,0,1]
	v_pk_fma_f32 v[242:243], v[124:125], v[206:207], v[242:243] op_sel:[0,1,0] op_sel_hi:[1,1,1]
	v_fmac_f32_e32 v241, v126, v240
	v_pk_fma_f32 v[242:243], v[128:129], v[240:241], v[242:243] op_sel:[0,0,0] op_sel_hi:[1,0,1]
	v_pk_fma_f32 v[242:243], v[130:131], v[240:241], v[242:243] op_sel:[0,1,0] op_sel_hi:[1,1,1]
	v_fmac_f32_e32 v243, v127, v242
	v_cndmask_b32_e64 v200, v240, v84, s[98:99]
	v_cndmask_b32_e64 v201, v241, v85, s[98:99]
	v_cndmask_b32_e64 v202, v242, v86, s[98:99]
	v_cndmask_b32_e64 v203, v243, v87, s[98:99]
	v_mov_b32_e32 v252, v240
	v_mov_b32_e32 v253, v241
	v_mov_b32_e32 v254, v242
	v_mov_b32_e32 v255, v243
	v_mfma_f32_16x16x4_f32 v[208:211], v184, v200, v[208:211]
	v_mfma_f32_16x16x4_f32 v[212:215], v188, v200, v[212:215]
	v_mfma_f32_16x16x4_f32 v[216:219], v192, v200, v[216:219]
	v_mfma_f32_16x16x4_f32 v[220:223], v196, v200, v[220:223]
	v_permlane32_swap_b32_e32 v252, v254
	v_permlane32_swap_b32_e32 v253, v255
	v_mfma_f32_16x16x4_f32 v[208:211], v185, v201, v[208:211]
	v_mfma_f32_16x16x4_f32 v[212:215], v189, v201, v[212:215]
	v_mfma_f32_16x16x4_f32 v[216:219], v193, v201, v[216:219]
	v_mfma_f32_16x16x4_f32 v[220:223], v197, v201, v[220:223]
	v_mfma_f32_16x16x4_f32 v[208:211], v186, v202, v[208:211]
	v_mfma_f32_16x16x4_f32 v[212:215], v190, v202, v[212:215]
	v_mfma_f32_16x16x4_f32 v[216:219], v194, v202, v[216:219]
	v_mfma_f32_16x16x4_f32 v[220:223], v198, v202, v[220:223]
	v_mfma_f32_16x16x4_f32 v[208:211], v187, v203, v[208:211]
	v_mfma_f32_16x16x4_f32 v[212:215], v191, v203, v[212:215]
	v_mfma_f32_16x16x4_f32 v[216:219], v195, v203, v[216:219]
	v_mfma_f32_16x16x4_f32 v[220:223], v199, v203, v[220:223]
	v_mfma_f32_16x16x4_f32 v[248:251], v82, v252, v[240:243]
	v_mfma_f32_16x16x4_f32 v[248:251], v83, v253, v[248:251]
	s_waitcnt lgkmcnt(3)
	s_nop 4
	v_pk_mul_f32 v[208:209], v[208:209], v[88:89]
	v_pk_mul_f32 v[210:211], v[210:211], v[90:91]
	s_nop 0
	v_mfma_f32_16x16x4_f32 v[72:75], v140, v208, v[72:75]
	s_waitcnt lgkmcnt(2)
	v_pk_mul_f32 v[212:213], v[212:213], v[92:93]
	v_mfma_f32_16x16x4_f32 v[244:247], v141, v209, 0
	v_pk_mul_f32 v[214:215], v[214:215], v[94:95]
	v_mfma_f32_16x16x4_f32 v[72:75], v142, v210, v[72:75]
	s_waitcnt lgkmcnt(1)
	v_pk_mul_f32 v[216:217], v[216:217], v[96:97]
	v_mfma_f32_16x16x4_f32 v[244:247], v143, v211, v[244:247]
	v_pk_mul_f32 v[218:219], v[218:219], v[98:99]
	v_mfma_f32_16x16x4_f32 v[72:75], v144, v212, v[72:75]
	s_waitcnt lgkmcnt(0)
	v_pk_mul_f32 v[220:221], v[220:221], v[100:101]
	v_mfma_f32_16x16x4_f32 v[244:247], v145, v213, v[244:247]
	v_pk_mul_f32 v[222:223], v[222:223], v[102:103]
	v_mfma_f32_16x16x4_f32 v[72:75], v146, v214, v[72:75]
	s_mov_b64 exec, s[98:99]
	ds_write_b32 v231, v248
	ds_write_b32 v231, v249 offset:256
	ds_write_b32 v231, v250 offset:512
	ds_write_b32 v231, v251 offset:768
	s_mov_b64 exec, -1
	ds_read_b128 v[184:187], v236 offset:14080
	ds_read_b128 v[188:191], v236 offset:15104
	v_mfma_f32_16x16x4_f32 v[244:247], v147, v215, v[244:247]
	ds_read_b128 v[192:195], v236 offset:16128
	ds_read_b128 v[196:199], v236 offset:17152
	v_mfma_f32_16x16x4_f32 v[72:75], v148, v216, v[72:75]
	ds_read_b64 v[80:81], v32
	ds_read_b64 v[82:83], v33
	ds_read_b32 v84, v230 offset:4096
	ds_read_b32 v85, v230 offset:4352
	v_mfma_f32_16x16x4_f32 v[244:247], v149, v217, v[244:247]
	ds_read_b32 v86, v230 offset:4608
	ds_read_b32 v87, v230 offset:4864
	ds_read_b32 v36, v239 offset:4096
	ds_read_b32 v37, v239 offset:4352
	v_mfma_f32_16x16x4_f32 v[72:75], v150, v218, v[72:75]
	ds_read_b128 v[88:91], v26
	ds_read_b128 v[92:95], v26 offset:1024
	ds_read_b128 v[96:99], v26 offset:2048
	ds_read_b128 v[100:103], v26 offset:3072
	v_mfma_f32_16x16x4_f32 v[244:247], v151, v219, v[244:247]
	ds_read_b32 v104, v29 offset:4
	ds_read_b32 v105, v29 offset:76
	ds_read_b64 v[106:107], v29 offset:8
	ds_read_b64 v[108:109], v29 offset:40
	v_mfma_f32_16x16x4_f32 v[72:75], v152, v220, v[72:75]
	ds_read_b32 v126, v31 offset:4
	ds_read_b32 v127, v31 offset:76
	ds_read_b64 v[128:129], v31 offset:8
	ds_read_b64 v[130:131], v31 offset:40
	v_mfma_f32_16x16x4_f32 v[244:247], v153, v221, v[244:247]
	ds_read_b64 v[110:111], v30
	ds_read_b64 v[112:113], v30 offset:32
	ds_read_b64 v[114:115], v30 offset:64
	ds_read_b64 v[116:117], v30 offset:96
	v_mfma_f32_16x16x4_f32 v[72:75], v154, v222, v[72:75]
	ds_read_b64 v[118:119], v30 offset:8
	ds_read_b64 v[120:121], v30 offset:40
	ds_read_b64 v[122:123], v30 offset:72
	ds_read_b64 v[124:125], v30 offset:104
	v_mfma_f32_16x16x4_f32 v[244:247], v155, v223, v[244:247]
	s_nop 9
	v_pk_add_f32 v[72:73], v[72:73], v[244:245]
	v_pk_add_f32 v[74:75], v[74:75], v[246:247]
	v_fmac_f32_e32 v73, v156, v72
	v_pk_fma_f32 v[74:75], v[158:159], v[72:73], v[74:75] op_sel:[0,0,0] op_sel_hi:[1,0,1]
	v_pk_fma_f32 v[74:75], v[160:161], v[72:73], v[74:75] op_sel:[0,1,0] op_sel_hi:[1,1,1]
	v_fmac_f32_e32 v75, v157, v74
	ds_bpermute_b32 v204, v232, v72
	ds_bpermute_b32 v205, v232, v73
	ds_bpermute_b32 v206, v232, v74
	ds_bpermute_b32 v207, v232, v75
	ds_read_b128 v[140:143], v226 offset:9984
	ds_read_b128 v[144:147], v226 offset:10048
	ds_read_b128 v[148:151], v226 offset:10112
	ds_read_b128 v[152:155], v226 offset:10176
	s_waitcnt lgkmcnt(15)
	v_mfma_f32_16x16x4_f32 v[240:243], v80, v36, 0
	v_mfma_f32_16x16x4_f32 v[240:243], v81, v37, v[240:243]
	s_waitcnt lgkmcnt(6)
	v_pk_fma_f32 v[72:73], v[162:163], v[204:205], v[72:73] op_sel:[0,0,0] op_sel_hi:[1,0,1]
	v_pk_fma_f32 v[72:73], v[164:165], v[204:205], v[72:73] op_sel:[0,1,0] op_sel_hi:[1,1,1]
	s_waitcnt lgkmcnt(4)
	v_pk_fma_f32 v[72:73], v[166:167], v[206:207], v[72:73] op_sel:[0,0,0] op_sel_hi:[1,0,1]
	v_pk_fma_f32 v[72:73], v[168:169], v[206:207], v[72:73] op_sel:[0,1,0] op_sel_hi:[1,1,1]
	v_pk_fma_f32 v[74:75], v[170:171], v[204:205], v[74:75] op_sel:[0,0,0] op_sel_hi:[1,0,1]
	v_pk_fma_f32 v[74:75], v[172:173], v[204:205], v[74:75] op_sel:[0,1,0] op_sel_hi:[1,1,1]
	v_pk_fma_f32 v[74:75], v[174:175], v[206:207], v[74:75] op_sel:[0,0,0] op_sel_hi:[1,0,1]
	v_pk_fma_f32 v[74:75], v[176:177], v[206:207], v[74:75] op_sel:[0,1,0] op_sel_hi:[1,1,1]
	v_fmac_f32_e32 v73, v178, v72
	v_pk_fma_f32 v[74:75], v[180:181], v[72:73], v[74:75] op_sel:[0,0,0] op_sel_hi:[1,0,1]
	v_pk_fma_f32 v[74:75], v[182:183], v[72:73], v[74:75] op_sel:[0,1,0] op_sel_hi:[1,1,1]
	v_fmac_f32_e32 v75, v179, v74
	v_cndmask_b32_e64 v200, v72, v136, s[98:99]
	v_cndmask_b32_e64 v201, v73, v137, s[98:99]
	v_cndmask_b32_e64 v202, v74, v138, s[98:99]
	v_cndmask_b32_e64 v203, v75, v139, s[98:99]
	v_mov_b32_e32 v252, v72
	v_mov_b32_e32 v253, v73
	v_mov_b32_e32 v254, v74
	v_mov_b32_e32 v255, v75
	v_mfma_f32_16x16x4_f32 v[208:211], v184, v200, v[208:211]
	v_mfma_f32_16x16x4_f32 v[212:215], v188, v200, v[212:215]
	v_mfma_f32_16x16x4_f32 v[216:219], v192, v200, v[216:219]
	v_mfma_f32_16x16x4_f32 v[220:223], v196, v200, v[220:223]
	v_permlane32_swap_b32_e32 v252, v254
	v_permlane32_swap_b32_e32 v253, v255
	v_mfma_f32_16x16x4_f32 v[208:211], v185, v201, v[208:211]
	v_mfma_f32_16x16x4_f32 v[212:215], v189, v201, v[212:215]
	v_mfma_f32_16x16x4_f32 v[216:219], v193, v201, v[216:219]
	v_mfma_f32_16x16x4_f32 v[220:223], v197, v201, v[220:223]
	v_mfma_f32_16x16x4_f32 v[208:211], v186, v202, v[208:211]
	v_mfma_f32_16x16x4_f32 v[212:215], v190, v202, v[212:215]
	v_mfma_f32_16x16x4_f32 v[216:219], v194, v202, v[216:219]
	v_mfma_f32_16x16x4_f32 v[220:223], v198, v202, v[220:223]
	v_mfma_f32_16x16x4_f32 v[208:211], v187, v203, v[208:211]
	v_mfma_f32_16x16x4_f32 v[212:215], v191, v203, v[212:215]
	v_mfma_f32_16x16x4_f32 v[216:219], v195, v203, v[216:219]
	v_mfma_f32_16x16x4_f32 v[220:223], v199, v203, v[220:223]
	v_mfma_f32_16x16x4_f32 v[248:251], v134, v252, v[72:75]
	v_mfma_f32_16x16x4_f32 v[248:251], v135, v253, v[248:251]
	s_waitcnt lgkmcnt(3)
	s_nop 4
	v_pk_mul_f32 v[208:209], v[208:209], v[140:141]
	v_pk_mul_f32 v[210:211], v[210:211], v[142:143]
	s_nop 0
	v_mfma_f32_16x16x4_f32 v[240:243], v88, v208, v[240:243]
	s_waitcnt lgkmcnt(2)
	v_pk_mul_f32 v[212:213], v[212:213], v[144:145]
	v_mfma_f32_16x16x4_f32 v[244:247], v89, v209, 0
	v_pk_mul_f32 v[214:215], v[214:215], v[146:147]
	v_mfma_f32_16x16x4_f32 v[240:243], v90, v210, v[240:243]
	s_waitcnt lgkmcnt(1)
	v_pk_mul_f32 v[216:217], v[216:217], v[148:149]
	v_mfma_f32_16x16x4_f32 v[244:247], v91, v211, v[244:247]
	v_pk_mul_f32 v[218:219], v[218:219], v[150:151]
	v_mfma_f32_16x16x4_f32 v[240:243], v92, v212, v[240:243]
	s_waitcnt lgkmcnt(0)
	v_pk_mul_f32 v[220:221], v[220:221], v[152:153]
	v_mfma_f32_16x16x4_f32 v[244:247], v93, v213, v[244:247]
	v_pk_mul_f32 v[222:223], v[222:223], v[154:155]
	v_mfma_f32_16x16x4_f32 v[240:243], v94, v214, v[240:243]
	s_mov_b64 exec, s[98:99]
	ds_write_b32 v231, v248 offset:2048
	ds_write_b32 v231, v249 offset:2304
	ds_write_b32 v231, v250 offset:2560
	ds_write_b32 v231, v251 offset:2816
	s_mov_b64 exec, -1
	ds_read_b128 v[184:187], v27 offset:4096
	ds_read_b128 v[188:191], v27 offset:5120
	v_mfma_f32_16x16x4_f32 v[244:247], v95, v215, v[244:247]
	ds_read_b128 v[192:195], v27 offset:6144
	ds_read_b128 v[196:199], v27 offset:7168
	v_mfma_f32_16x16x4_f32 v[240:243], v96, v216, v[240:243]
	ds_read_b64 v[132:133], v32 offset:9984
	ds_read_b64 v[134:135], v33 offset:9984
	ds_read_b32 v136, v230 offset:6144
	ds_read_b32 v137, v230 offset:6400
	v_mfma_f32_16x16x4_f32 v[244:247], v97, v217, v[244:247]
	ds_read_b32 v138, v230 offset:6656
	ds_read_b32 v139, v230 offset:6912
	ds_read_b32 v38, v239 offset:6144
	ds_read_b32 v39, v239 offset:6400
	v_mfma_f32_16x16x4_f32 v[240:243], v98, v218, v[240:243]
	ds_read_b128 v[140:143], v26 offset:9984
	ds_read_b128 v[144:147], v26 offset:11008
	ds_read_b128 v[148:151], v26 offset:12032
	ds_read_b128 v[152:155], v26 offset:13056
	v_mfma_f32_16x16x4_f32 v[244:247], v99, v219, v[244:247]
	ds_read_b32 v156, v29 offset:9988
	ds_read_b32 v157, v29 offset:10060
	ds_read_b64 v[158:159], v29 offset:9992
	ds_read_b64 v[160:161], v29 offset:10024
	v_mfma_f32_16x16x4_f32 v[240:243], v100, v220, v[240:243]
	ds_read_b32 v178, v31 offset:9988
	ds_read_b32 v179, v31 offset:10060
	ds_read_b64 v[180:181], v31 offset:9992
	ds_read_b64 v[182:183], v31 offset:10024
	v_mfma_f32_16x16x4_f32 v[244:247], v101, v221, v[244:247]
	ds_read_b64 v[162:163], v30 offset:9984
	ds_read_b64 v[164:165], v30 offset:10016
	ds_read_b64 v[166:167], v30 offset:10048
	ds_read_b64 v[168:169], v30 offset:10080
	v_mfma_f32_16x16x4_f32 v[240:243], v102, v222, v[240:243]
	ds_read_b64 v[170:171], v30 offset:9992
	ds_read_b64 v[172:173], v30 offset:10024
	ds_read_b64 v[174:175], v30 offset:10056
	ds_read_b64 v[176:177], v30 offset:10088
	v_mfma_f32_16x16x4_f32 v[244:247], v103, v223, v[244:247]
	s_nop 9
	v_pk_add_f32 v[240:241], v[240:241], v[244:245]
	v_pk_add_f32 v[242:243], v[242:243], v[246:247]
	v_fmac_f32_e32 v241, v104, v240
	v_pk_fma_f32 v[242:243], v[106:107], v[240:241], v[242:243] op_sel:[0,0,0] op_sel_hi:[1,0,1]
	v_pk_fma_f32 v[242:243], v[108:109], v[240:241], v[242:243] op_sel:[0,1,0] op_sel_hi:[1,1,1]
	v_fmac_f32_e32 v243, v105, v242
	ds_bpermute_b32 v204, v232, v240
	ds_bpermute_b32 v205, v232, v241
	ds_bpermute_b32 v206, v232, v242
	ds_bpermute_b32 v207, v232, v243
	ds_read_b128 v[88:91], v28
	ds_read_b128 v[92:95], v28 offset:64
	ds_read_b128 v[96:99], v28 offset:128
	ds_read_b128 v[100:103], v28 offset:192
	s_waitcnt lgkmcnt(15)
	v_mfma_f32_16x16x4_f32 v[72:75], v132, v38, 0
	v_mfma_f32_16x16x4_f32 v[72:75], v133, v39, v[72:75]
	s_waitcnt lgkmcnt(6)
	v_pk_fma_f32 v[240:241], v[110:111], v[204:205], v[240:241] op_sel:[0,0,0] op_sel_hi:[1,0,1]
	v_pk_fma_f32 v[240:241], v[112:113], v[204:205], v[240:241] op_sel:[0,1,0] op_sel_hi:[1,1,1]
	s_waitcnt lgkmcnt(4)
	v_pk_fma_f32 v[240:241], v[114:115], v[206:207], v[240:241] op_sel:[0,0,0] op_sel_hi:[1,0,1]
	v_pk_fma_f32 v[240:241], v[116:117], v[206:207], v[240:241] op_sel:[0,1,0] op_sel_hi:[1,1,1]
	v_pk_fma_f32 v[242:243], v[118:119], v[204:205], v[242:243] op_sel:[0,0,0] op_sel_hi:[1,0,1]
	v_pk_fma_f32 v[242:243], v[120:121], v[204:205], v[242:243] op_sel:[0,1,0] op_sel_hi:[1,1,1]
	v_pk_fma_f32 v[242:243], v[122:123], v[206:207], v[242:243] op_sel:[0,0,0] op_sel_hi:[1,0,1]
	v_pk_fma_f32 v[242:243], v[124:125], v[206:207], v[242:243] op_sel:[0,1,0] op_sel_hi:[1,1,1]
	v_fmac_f32_e32 v241, v126, v240
	v_pk_fma_f32 v[242:243], v[128:129], v[240:241], v[242:243] op_sel:[0,0,0] op_sel_hi:[1,0,1]
	v_pk_fma_f32 v[242:243], v[130:131], v[240:241], v[242:243] op_sel:[0,1,0] op_sel_hi:[1,1,1]
	v_fmac_f32_e32 v243, v127, v242
	v_cndmask_b32_e64 v200, v240, v84, s[98:99]
	v_cndmask_b32_e64 v201, v241, v85, s[98:99]
	v_cndmask_b32_e64 v202, v242, v86, s[98:99]
	v_cndmask_b32_e64 v203, v243, v87, s[98:99]
	v_mov_b32_e32 v252, v240
	v_mov_b32_e32 v253, v241
	v_mov_b32_e32 v254, v242
	v_mov_b32_e32 v255, v243
	v_mfma_f32_16x16x4_f32 v[208:211], v184, v200, v[208:211]
	v_mfma_f32_16x16x4_f32 v[212:215], v188, v200, v[212:215]
	v_mfma_f32_16x16x4_f32 v[216:219], v192, v200, v[216:219]
	v_mfma_f32_16x16x4_f32 v[220:223], v196, v200, v[220:223]
	v_permlane32_swap_b32_e32 v252, v254
	v_permlane32_swap_b32_e32 v253, v255
	v_mfma_f32_16x16x4_f32 v[208:211], v185, v201, v[208:211]
	v_mfma_f32_16x16x4_f32 v[212:215], v189, v201, v[212:215]
	v_mfma_f32_16x16x4_f32 v[216:219], v193, v201, v[216:219]
	v_mfma_f32_16x16x4_f32 v[220:223], v197, v201, v[220:223]
	v_mfma_f32_16x16x4_f32 v[208:211], v186, v202, v[208:211]
	v_mfma_f32_16x16x4_f32 v[212:215], v190, v202, v[212:215]
	v_mfma_f32_16x16x4_f32 v[216:219], v194, v202, v[216:219]
	v_mfma_f32_16x16x4_f32 v[220:223], v198, v202, v[220:223]
	v_mfma_f32_16x16x4_f32 v[208:211], v187, v203, v[208:211]
	v_mfma_f32_16x16x4_f32 v[212:215], v191, v203, v[212:215]
	v_mfma_f32_16x16x4_f32 v[216:219], v195, v203, v[216:219]
	v_mfma_f32_16x16x4_f32 v[220:223], v199, v203, v[220:223]
	v_mfma_f32_16x16x4_f32 v[248:251], v82, v252, v[240:243]
	v_mfma_f32_16x16x4_f32 v[248:251], v83, v253, v[248:251]
	s_waitcnt lgkmcnt(3)
	s_nop 4
	v_pk_mul_f32 v[208:209], v[208:209], v[88:89]
	v_pk_mul_f32 v[210:211], v[210:211], v[90:91]
	s_nop 0
	v_mfma_f32_16x16x4_f32 v[72:75], v140, v208, v[72:75]
	s_waitcnt lgkmcnt(2)
	v_pk_mul_f32 v[212:213], v[212:213], v[92:93]
	v_mfma_f32_16x16x4_f32 v[244:247], v141, v209, 0
	v_pk_mul_f32 v[214:215], v[214:215], v[94:95]
	v_mfma_f32_16x16x4_f32 v[72:75], v142, v210, v[72:75]
	s_waitcnt lgkmcnt(1)
	v_pk_mul_f32 v[216:217], v[216:217], v[96:97]
	v_mfma_f32_16x16x4_f32 v[244:247], v143, v211, v[244:247]
	v_pk_mul_f32 v[218:219], v[218:219], v[98:99]
	v_mfma_f32_16x16x4_f32 v[72:75], v144, v212, v[72:75]
	s_waitcnt lgkmcnt(0)
	v_pk_mul_f32 v[220:221], v[220:221], v[100:101]
	v_mfma_f32_16x16x4_f32 v[244:247], v145, v213, v[244:247]
	v_pk_mul_f32 v[222:223], v[222:223], v[102:103]
	v_mfma_f32_16x16x4_f32 v[72:75], v146, v214, v[72:75]
	s_mov_b64 exec, s[98:99]
	ds_write_b32 v231, v248 offset:4096
	ds_write_b32 v231, v249 offset:4352
	ds_write_b32 v231, v250 offset:4608
	ds_write_b32 v231, v251 offset:4864
	s_mov_b64 exec, -1
	ds_read_b128 v[184:187], v27 offset:14080
	ds_read_b128 v[188:191], v27 offset:15104
	v_mfma_f32_16x16x4_f32 v[244:247], v147, v215, v[244:247]
	ds_read_b128 v[192:195], v27 offset:16128
	ds_read_b128 v[196:199], v27 offset:17152
	v_mfma_f32_16x16x4_f32 v[72:75], v148, v216, v[72:75]
	v_mfma_f32_16x16x4_f32 v[244:247], v149, v217, v[244:247]
	v_mfma_f32_16x16x4_f32 v[72:75], v150, v218, v[72:75]
	v_mfma_f32_16x16x4_f32 v[244:247], v151, v219, v[244:247]
	v_mfma_f32_16x16x4_f32 v[72:75], v152, v220, v[72:75]
	v_mfma_f32_16x16x4_f32 v[244:247], v153, v221, v[244:247]
	v_mfma_f32_16x16x4_f32 v[72:75], v154, v222, v[72:75]
	v_mfma_f32_16x16x4_f32 v[244:247], v155, v223, v[244:247]
	s_nop 9
	v_pk_add_f32 v[72:73], v[72:73], v[244:245]
	v_pk_add_f32 v[74:75], v[74:75], v[246:247]
	v_fmac_f32_e32 v73, v156, v72
	v_pk_fma_f32 v[74:75], v[158:159], v[72:73], v[74:75] op_sel:[0,0,0] op_sel_hi:[1,0,1]
	v_pk_fma_f32 v[74:75], v[160:161], v[72:73], v[74:75] op_sel:[0,1,0] op_sel_hi:[1,1,1]
	v_fmac_f32_e32 v75, v157, v74
	ds_bpermute_b32 v204, v232, v72
	ds_bpermute_b32 v205, v232, v73
	ds_bpermute_b32 v206, v232, v74
	ds_bpermute_b32 v207, v232, v75
	ds_read_b128 v[140:143], v28 offset:9984
	ds_read_b128 v[144:147], v28 offset:10048
	ds_read_b128 v[148:151], v28 offset:10112
	ds_read_b128 v[152:155], v28 offset:10176
	s_waitcnt lgkmcnt(6)
	v_pk_fma_f32 v[72:73], v[162:163], v[204:205], v[72:73] op_sel:[0,0,0] op_sel_hi:[1,0,1]
	v_pk_fma_f32 v[72:73], v[164:165], v[204:205], v[72:73] op_sel:[0,1,0] op_sel_hi:[1,1,1]
	s_waitcnt lgkmcnt(4)
	v_pk_fma_f32 v[72:73], v[166:167], v[206:207], v[72:73] op_sel:[0,0,0] op_sel_hi:[1,0,1]
	v_pk_fma_f32 v[72:73], v[168:169], v[206:207], v[72:73] op_sel:[0,1,0] op_sel_hi:[1,1,1]
	v_pk_fma_f32 v[74:75], v[170:171], v[204:205], v[74:75] op_sel:[0,0,0] op_sel_hi:[1,0,1]
	v_pk_fma_f32 v[74:75], v[172:173], v[204:205], v[74:75] op_sel:[0,1,0] op_sel_hi:[1,1,1]
	v_pk_fma_f32 v[74:75], v[174:175], v[206:207], v[74:75] op_sel:[0,0,0] op_sel_hi:[1,0,1]
	v_pk_fma_f32 v[74:75], v[176:177], v[206:207], v[74:75] op_sel:[0,1,0] op_sel_hi:[1,1,1]
	v_fmac_f32_e32 v73, v178, v72
	v_pk_fma_f32 v[74:75], v[180:181], v[72:73], v[74:75] op_sel:[0,0,0] op_sel_hi:[1,0,1]
	v_pk_fma_f32 v[74:75], v[182:183], v[72:73], v[74:75] op_sel:[0,1,0] op_sel_hi:[1,1,1]
	v_fmac_f32_e32 v75, v179, v74
	v_cndmask_b32_e64 v200, v72, v136, s[98:99]
	v_cndmask_b32_e64 v201, v73, v137, s[98:99]
	v_cndmask_b32_e64 v202, v74, v138, s[98:99]
	v_cndmask_b32_e64 v203, v75, v139, s[98:99]
	v_mov_b32_e32 v252, v72
	v_mov_b32_e32 v253, v73
	v_mov_b32_e32 v254, v74
	v_mov_b32_e32 v255, v75
	v_mfma_f32_16x16x4_f32 v[208:211], v184, v200, v[208:211]
	v_mfma_f32_16x16x4_f32 v[212:215], v188, v200, v[212:215]
	v_mfma_f32_16x16x4_f32 v[216:219], v192, v200, v[216:219]
	v_mfma_f32_16x16x4_f32 v[220:223], v196, v200, v[220:223]
	v_permlane32_swap_b32_e32 v252, v254
	v_permlane32_swap_b32_e32 v253, v255
	v_mfma_f32_16x16x4_f32 v[208:211], v185, v201, v[208:211]
	v_mfma_f32_16x16x4_f32 v[212:215], v189, v201, v[212:215]
	v_mfma_f32_16x16x4_f32 v[216:219], v193, v201, v[216:219]
	v_mfma_f32_16x16x4_f32 v[220:223], v197, v201, v[220:223]
	v_mfma_f32_16x16x4_f32 v[208:211], v186, v202, v[208:211]
	v_mfma_f32_16x16x4_f32 v[212:215], v190, v202, v[212:215]
	v_mfma_f32_16x16x4_f32 v[216:219], v194, v202, v[216:219]
	v_mfma_f32_16x16x4_f32 v[220:223], v198, v202, v[220:223]
	v_mfma_f32_16x16x4_f32 v[208:211], v187, v203, v[208:211]
	v_mfma_f32_16x16x4_f32 v[212:215], v191, v203, v[212:215]
	v_mfma_f32_16x16x4_f32 v[216:219], v195, v203, v[216:219]
	v_mfma_f32_16x16x4_f32 v[220:223], v199, v203, v[220:223]
	v_mfma_f32_16x16x4_f32 v[248:251], v134, v252, v[72:75]
	v_mfma_f32_16x16x4_f32 v[248:251], v135, v253, v[248:251]
	s_waitcnt lgkmcnt(3)
	s_nop 4
	v_pk_mul_f32 v[208:209], v[208:209], v[140:141]
	v_pk_mul_f32 v[210:211], v[210:211], v[142:143]
	s_waitcnt lgkmcnt(2)
	v_pk_mul_f32 v[212:213], v[212:213], v[144:145]
	v_pk_mul_f32 v[214:215], v[214:215], v[146:147]
	s_waitcnt lgkmcnt(1)
	v_pk_mul_f32 v[216:217], v[216:217], v[148:149]
	v_pk_mul_f32 v[218:219], v[218:219], v[150:151]
	s_waitcnt lgkmcnt(0)
	v_pk_mul_f32 v[220:221], v[220:221], v[152:153]
	v_pk_mul_f32 v[222:223], v[222:223], v[154:155]
	s_mov_b64 exec, s[98:99]
	ds_write_b32 v231, v248 offset:6144
	ds_write_b32 v231, v249 offset:6400
	ds_write_b32 v231, v250 offset:6656
	ds_write_b32 v231, v251 offset:6912
	s_mov_b64 exec, -1
	s_branch .LBB0_655

.Lmy_ck_drE_h:
	s_waitcnt lgkmcnt(0)
	s_bfe_u32 s96, s62, 0x20006
	s_and_b32 s97, s96, 1
	s_mul_i32 s97, s97, 0x2700
	s_mov_b32 s101, 0x1c000
	s_mov_b32 s100, 0x6100
	s_bitcmp0_b32 s65, 0
	s_cselect_b32 s101, 0xe000, s101
	s_cselect_b32 s100, 0x4e00, s100
	s_cmp_gt_u32 s96, 1
	s_cselect_b32 s100, s100, 0
	s_add_i32 s97, s97, s101
	s_add_i32 s97, s97, s100
	s_mov_b32 s96, s97
	v_and_b32_e32 v72, 3, v233
	v_lshrrev_b32_e32 v73, 2, v233
	v_lshlrev_b32_e32 v72, 2, v72
	v_lshl_add_u32 v72, v73, 8, v72
	v_lshl_add_u32 v72, v234, 6, v72
	s_add_i32 s97, s96, 0x1000
	v_add_u32_e32 v78, s97, v72
	v_xor_b32_e32 v79, v224, v234
	v_lshl_add_u32 v79, v79, 4, s96
	ds_read_b128 v[96:99], v79
	ds_read_b128 v[100:103], v79 offset:1024
	ds_read_b128 v[104:107], v79 offset:2048
	ds_read_b128 v[108:111], v79 offset:3072
	ds_read_b32 v80, v78
	ds_read_b32 v81, v78 offset:16
	ds_read_b32 v82, v78 offset:32
	ds_read_b32 v83, v78 offset:48
	ds_read_b32 v84, v78 offset:1024
	ds_read_b32 v85, v78 offset:1040
	ds_read_b32 v86, v78 offset:1056
	ds_read_b32 v87, v78 offset:1072
	ds_read_b32 v88, v78 offset:2048
	ds_read_b32 v89, v78 offset:2064
	ds_read_b32 v90, v78 offset:2080
	ds_read_b32 v91, v78 offset:2096
	ds_read_b32 v92, v78 offset:3072
	ds_read_b32 v93, v78 offset:3088
	ds_read_b32 v94, v78 offset:3104
	ds_read_b32 v95, v78 offset:3120
	v_lshl_add_u32 v74, v224, 2, s96
	ds_write_b32 v74, v235 offset:9728
	v_add_u32_e32 v75, -1, v233
	v_mov_b32_e32 v76, -1
	v_cndmask_b32_e64 v75, v76, v75, s[98:99]
	v_cmp_lt_u32_e64 s[100:101], 7, v233
	v_add_u32_e32 v76, -8, v233
	v_and_b32_e32 v77, 1, v234
	v_cndmask_b32_e64 v75, v75, v76, s[100:101]
	v_lshlrev_b32_e32 v77, 2, v77
	v_sub_u32_e32 v76, v75, v77
	v_lshlrev_b32_e32 v77, 2, v234
	v_sub_u32_e32 v77, v233, v77
	v_add_u32_e32 v77, -1, v77
	s_waitcnt lgkmcnt(15)
	v_mfma_f32_16x16x4_f32 v[244:247], v80, v96, 0
	v_mfma_f32_16x16x4_f32 v[240:243], v81, v97, 0
	s_waitcnt lgkmcnt(14)
	v_mfma_f32_16x16x4_f32 v[244:247], v82, v98, v[244:247]
	s_waitcnt lgkmcnt(13)
	v_mfma_f32_16x16x4_f32 v[240:243], v83, v99, v[240:243]
	s_waitcnt lgkmcnt(12)
	v_mfma_f32_16x16x4_f32 v[244:247], v84, v100, v[244:247]
	s_waitcnt lgkmcnt(11)
	v_mfma_f32_16x16x4_f32 v[240:243], v85, v101, v[240:243]
	s_waitcnt lgkmcnt(10)
	v_mfma_f32_16x16x4_f32 v[244:247], v86, v102, v[244:247]
	s_waitcnt lgkmcnt(9)
	v_mfma_f32_16x16x4_f32 v[240:243], v87, v103, v[240:243]
	s_waitcnt lgkmcnt(8)
	v_mfma_f32_16x16x4_f32 v[244:247], v88, v104, v[244:247]
	s_waitcnt lgkmcnt(7)
	v_mfma_f32_16x16x4_f32 v[240:243], v89, v105, v[240:243]
	s_waitcnt lgkmcnt(6)
	v_mfma_f32_16x16x4_f32 v[244:247], v90, v106, v[244:247]
	s_waitcnt lgkmcnt(5)
	v_mfma_f32_16x16x4_f32 v[240:243], v91, v107, v[240:243]
	s_waitcnt lgkmcnt(4)
	v_mfma_f32_16x16x4_f32 v[244:247], v92, v108, v[244:247]
	s_waitcnt lgkmcnt(3)
	v_mfma_f32_16x16x4_f32 v[240:243], v93, v109, v[240:243]
	s_waitcnt lgkmcnt(2)
	v_mfma_f32_16x16x4_f32 v[244:247], v94, v110, v[244:247]
	s_waitcnt lgkmcnt(1)
	v_mfma_f32_16x16x4_f32 v[240:243], v95, v111, v[240:243]
	s_nop 9
	v_add_f32_e32 v244, v244, v240
	v_add_f32_e32 v245, v245, v241
	v_add_f32_e32 v246, v246, v242
	v_add_f32_e32 v247, v247, v243
	v_cmp_le_i32_e64 s[96:97], 0, v76
	v_cmp_le_i32_e64 s[100:101], 1, v76
	s_nop 0
	v_cndmask_b32_e64 v128, 0, v244, s[96:97]
	v_cndmask_b32_e64 v129, 0, v245, s[100:101]
	v_cmp_le_i32_e64 s[96:97], 2, v76
	v_cmp_le_i32_e64 s[100:101], 3, v76
	s_nop 0
	v_cndmask_b32_e64 v130, 0, v246, s[96:97]
	v_cndmask_b32_e64 v131, 0, v247, s[100:101]
	s_bfe_u32 s96, s62, 0x20006
	s_and_b32 s97, s96, 1
	s_mul_i32 s97, s97, 0x2700
	s_mov_b32 s101, 0x1c000
	s_mov_b32 s100, 0x6100
	s_bitcmp0_b32 s65, 0
	s_cselect_b32 s101, 0xe000, s101
	s_cselect_b32 s100, 0x4e00, s100
	s_cmp_gt_u32 s96, 1
	s_cselect_b32 s100, s100, 0
	s_add_i32 s97, s97, s101
	s_add_i32 s97, s97, s100
	v_xor_b32_e32 v74, v224, v234
	v_lshl_add_u32 v74, v74, 4, s97
	ds_write_b128 v74, v[128:131] offset:8448
	v_lshlrev_b32_e32 v75, 7, v234
	v_lshl_add_u32 v75, v233, 2, v75
	v_add_u32_e32 v75, s97, v75
	v_cmp_le_i32_e64 s[96:97], 0, v77
	v_cmp_le_i32_e64 s[100:101], 1, v77
	s_nop 0
	v_cndmask_b32_e64 v132, 0, v244, s[96:97]
	v_cndmask_b32_e64 v133, 0, v245, s[100:101]
	v_cmp_le_i32_e64 s[96:97], 2, v77
	v_cmp_le_i32_e64 s[100:101], 3, v77
	s_nop 0
	v_cndmask_b32_e64 v134, 0, v246, s[96:97]
	v_cndmask_b32_e64 v135, 0, v247, s[100:101]
	s_mov_b64 exec, 0x00ff00ff
	ds_write_b32 v75, v132 offset:9472
	ds_write_b32 v75, v133 offset:9504
	ds_write_b32 v75, v134 offset:9536
	ds_write_b32 v75, v135 offset:9568
	s_mov_b64 exec, -1
	s_setprio 0
	s_branch .LBB0_655
	s_nop 0
	s_nop 0
	s_nop 0
	s_nop 0
	s_nop 0
	s_nop 0
	s_nop 0
	s_nop 0
	s_nop 0
	s_nop 0
	s_nop 0
	s_nop 0
	s_nop 0
	s_nop 0
	s_nop 0
	s_nop 0
	s_nop 0
	s_nop 0
	s_nop 0
	s_nop 0
	s_nop 0
	s_nop 0
	s_nop 0
	s_nop 0
	s_nop 0
	s_nop 0
	s_nop 0
	s_nop 0
	s_nop 0
	s_nop 0
	s_nop 0
	s_nop 0
	s_nop 0
	s_nop 0
	s_nop 0
